# pass A prologue: remaining first-step DPP sums fused (v_add_f32_dpp), bf16 pair interleave via v_perm_b32 instead of and/shift/or_sdwa
# baseline (speedup 1.0000x reference)
.LBB0_661:
	v_writelane_b32 v233, s72, 28
	s_add_u32 s10, s86, 0x16b00000
	s_addc_u32 s11, s87, 0
	v_writelane_b32 v233, s73, 29
	v_writelane_b32 v233, s57, 30
	v_writelane_b32 v233, s71, 31
	s_add_u32 s0, s86, 0x1cd00000
	v_writelane_b32 v233, s0, 32
	s_addc_u32 s0, s87, 0
	v_writelane_b32 v233, s0, 33
	s_add_u32 s0, s84, 0x2000000
	s_addc_u32 s1, s85, 0
	s_add_u32 s50, s86, 0x1f700000
	v_writelane_b32 v233, s0, 34
	s_addc_u32 s51, s87, 0
	s_mov_b32 s73, 0x5040100
	v_writelane_b32 v233, s1, 35
	s_add_u32 s0, s86, 0x1f800000
	s_addc_u32 s1, s87, 0
	v_writelane_b32 v233, s0, 36
	s_ashr_i32 s71, s70, 31
	s_mov_b64 s[42:43], s[70:71]
	v_writelane_b32 v233, s1, 37
	s_ashr_i32 s0, s41, 31
	v_writelane_b32 v233, s0, 38
	s_lshl_b32 s0, s42, 5
	v_readlane_b32 s13, v233, 5
	s_and_b32 s15, s0, 0x60
	s_lshl_b32 s0, s13, 8
	s_add_i32 s48, 0, 0x12000
	s_ashr_i32 s14, s70, 3
	s_add_i32 s49, s48, s0
	s_cmp_lt_u32 s74, 64
	s_cselect_b64 s[24:25], -1, 0
	s_cmp_gt_u32 s74, 63
	s_cselect_b64 s[26:27], -1, 0
	s_cmpk_gt_u32 s74, 0x7f
	s_cselect_b64 s[0:1], -1, 0
	v_writelane_b32 v233, s0, 39
	s_cmpk_gt_u32 s74, 0xbf
	s_mul_i32 s4, s13, 0x480
	v_writelane_b32 v233, s1, 40
	s_cselect_b64 s[0:1], -1, 0
	v_writelane_b32 v233, s0, 41
	s_cmpk_gt_u32 s74, 0xff
	v_mov_b32_e32 v3, 0
	v_writelane_b32 v233, s1, 42
	s_cselect_b64 s[0:1], -1, 0
	v_writelane_b32 v233, s0, 43
	s_cmpk_gt_u32 s74, 0x13f
	s_waitcnt vmcnt(0)
	v_perm_b32 v88, v47, v0, s73
	v_writelane_b32 v233, s1, 44
	s_cselect_b64 s[0:1], -1, 0
	v_writelane_b32 v233, s0, 45
	s_cmpk_gt_u32 s74, 0x17f
	v_mov_b32_e32 v77, 0x260
	v_writelane_b32 v233, s1, 46
	s_cselect_b64 s[0:1], -1, 0
	v_writelane_b32 v233, s0, 47
	s_cmpk_gt_u32 s74, 0x1bf
	s_movk_i32 s76, 0x90
	v_writelane_b32 v233, s1, 48
	s_cselect_b64 s[0:1], -1, 0
	v_writelane_b32 v233, s0, 49
	s_cmpk_gt_u32 s74, 0x1ff
	v_mov_b64_e32 v[20:21], 0x1000
	v_writelane_b32 v233, s1, 50
	s_cselect_b64 s[0:1], -1, 0
	s_lshl_b32 s88, s13, 4
	v_writelane_b32 v233, s0, 51
	s_add_i32 s53, s88, 0
	s_lshr_b32 s5, s74, 7
	s_bfe_u32 s6, s74, 0x10006
	v_writelane_b32 v233, s1, 52
	s_cmpk_lt_u32 s74, 0x100
	s_mov_b32 s1, 0x9000
	s_cselect_b32 s0, 0, 0x2400
	s_cselect_b32 s7, s1, 0x1ce00
	s_movk_i32 s1, 0x4800
	s_cselect_b32 s8, s1, 0x6c00
	s_add_i32 s54, s0, 0
	s_bitcmp0_b32 s74, 7
	s_cselect_b32 s0, s1, 0x6c00
	s_add_i32 s55, s0, 0
	s_lshl_b32 s9, s6, 1
	s_cmpk_lt_u32 s74, 0x80
	s_cselect_b64 s[28:29], -1, 0
	s_cmp_eq_u32 s5, 2
	s_mov_b32 s0, 0x17200
	s_cselect_b32 s12, s0, 0x19600
	s_cmp_eq_u32 s5, 1
	s_cselect_b64 s[20:21], -1, 0
	s_and_b64 s[0:1], s[20:21], exec
	s_cselect_b32 s0, 0x14e00, s12
	s_add_i32 s56, s0, 0
	s_lshl_b32 s57, s6, 5
	s_lshl_b32 s58, s6, 6
	s_and_b32 s0, 64, s74
	s_cmp_eq_u32 s6, 0
	s_cselect_b64 s[30:31], -1, 0
	s_cmp_lg_u32 s0, 0
	s_cselect_b64 s[34:35], -1, 0
	s_or_b32 s62, s9, 1
	s_lshl_b32 s60, s62, 4
	s_lshl_b32 s61, s62, 5
	s_cmp_lg_u32 s13, 1
	s_mul_i32 s0, s13, 0x300
	s_cselect_b64 s[36:37], -1, 0
	s_add_i32 s64, s0, 0
	s_sub_i32 s63, s88, 64
	s_add_i32 s64, s64, 0x1ba00
	s_lshl_b32 s65, s13, 5
	s_cmpk_lt_u32 s74, 0xc0
	v_writelane_b32 v233, s74, 53
	s_cselect_b64 s[38:39], -1, 0
	s_add_i32 s0, s88, 16
	v_writelane_b32 v233, s0, 54
	s_lshl_b32 s0, s6, 3
	s_add_i32 s71, s0, 0
	s_lshl_b32 s0, s42, 9
	s_and_b32 s0, s0, 0x800
	v_writelane_b32 v233, s14, 56
	s_add_i32 s0, s14, s0
	v_writelane_b32 v233, s15, 57
	s_add_i32 s75, s0, s15
	s_load_dwordx2 s[40:41], s[82:83], 0x58
	s_load_dwordx4 s[12:15], s[82:83], 0x88
	s_lshl_b32 s69, s63, 1
	s_add_i32 s70, s69, 0
	s_lshl_b32 s1, s5, 6
	v_cndmask_b32_e64 v69, 0, 1, s[20:21]
	s_mul_i32 s59, s6, 0xa00
	s_mulk_i32 s62, 0x500
	s_add_i32 s66, s7, 0
	s_add_i32 s67, s8, 0
	s_and_b32 s68, s88, 48
	s_add_i32 s70, s70, 0x1ce00
	s_add_i32 s71, s71, s1
	s_add_i32 s72, s48, s65
	s_add_i32 s74, s4, 0
	s_add_i32 s77, 0, 0xfc00
	v_mov_b32_e32 v78, 0xf800000
	v_mov_b32_e32 v79, 0x4f800000
	v_mov_b32_e32 v124, v3
	v_mov_b32_e32 v125, v3
	v_mov_b32_e32 v80, 0x1e800
	v_mov_b32_e32 v81, 0x14400
	v_mov_b32_e32 v82, 0x900
	v_mov_b32_e32 v83, 0x1200
	v_mov_b32_e32 v87, 0x1b00
	s_mov_b32 s78, 0
	v_writelane_b32 v233, s42, 58
	s_mov_b32 s16, 0
	s_nop 0
	v_writelane_b32 v233, s43, 59
	v_mov_b32_e32 v213, v23
	v_ashrrev_i32_e32 v214, 3, v213
	v_add_u32_e32 v215, s33, v214
	v_mul_lo_u32 v216, v215, s76
	v_lshlrev_b32_e32 v217, 4, v213
	v_and_b32_e32 v218, 0x70, v217
	v_add3_u32 v130, 0, v216, v218
	v_mov_b32_e32 v213, v23
	v_and_b32_e32 v214, 0xffffff0, v213
	v_mul_lo_u32 v215, v214, s76
	v_lshlrev_b32_e32 v216, 1, v213
	v_add3_u32 v131, 0, v215, v216
	v_mov_b32_e32 v213, v23
	v_and_b32_e32 v214, 15, v213
	v_or_b32_e32 v215, s63, v214
	v_mul_lo_u32 v216, v215, s76
	v_and_b32_e32 v217, -16, v213
	v_add3_u32 v132, 0, v216, v217
	s_add_i32 s90, 0, 0x14e00
	v_mov_b32_e32 v213, v23
	v_ashrrev_i32_e32 v214, 3, v213
	v_add_u32_e32 v215, s33, v214
	v_mul_lo_u32 v216, v215, s76
	v_lshlrev_b32_e32 v217, 4, v213
	v_and_b32_e32 v218, 0x70, v217
	v_add3_u32 v133, s90, v216, v218
	s_add_i32 s91, 0, 0x14e00
	v_mov_b32_e32 v213, v23
	v_and_b32_e32 v214, 15, v213
	v_mul_u32_u24_e32 v215, 0x90, v214
	v_and_b32_e32 v216, -16, v213
	v_add3_u32 v134, s91, v215, v216
	s_add_i32 s92, 0, 0x1ba00
	v_mov_b32_e32 v213, v23
	v_ashrrev_i32_e32 v214, 4, v213
	s_movk_i32 s93, 0x300
	v_mul_lo_u32 v215, v214, s93
	v_and_b32_e32 v216, 15, v213
	v_mul_u32_u24_e32 v217, 48, v216
	v_add3_u32 v135, s92, v215, v217
	s_add_i32 s94, 0, 0x1ce00
	v_mov_b32_e32 v213, v23
	v_ashrrev_i32_e32 v214, 3, v213
	v_add_u32_e32 v215, s33, v214
	v_mul_lo_u32 v216, v215, s76
	v_lshlrev_b32_e32 v217, 4, v213
	v_and_b32_e32 v218, 0x70, v217
	v_add3_u32 v136, s94, v216, v218
	s_add_i32 s95, 0, 0x1ce00
	v_mov_b32_e32 v213, v23
	v_and_b32_e32 v214, 15, v213
	v_or_b32_e32 v215, s63, v214
	v_mul_lo_u32 v216, v215, s76
	v_ashrrev_i32_e32 v217, 4, v213
	v_lshlrev_b32_e32 v218, 3, v217
	v_add3_u32 v138, s95, v216, v218
	v_mov_b32_e32 v213, v23
	v_ashrrev_i32_e32 v214, 3, v213
	v_add_u32_e32 v215, s33, v214
	v_mul_lo_u32 v216, v215, s76
	v_lshlrev_b32_e32 v217, 4, v213
	v_and_b32_e32 v218, 0x70, v217
	v_add3_u32 v139, s48, v216, v218
	v_mov_b32_e32 v213, v23
	v_and_b32_e32 v214, 15, v213
	v_or_b32_e32 v215, s57, v214
	v_mul_u32_u24_e32 v216, 0x90, v215
	v_and_b32_e32 v217, -16, v213
	v_add3_u32 v140, s54, v216, v217
	v_mov_b32_e32 v213, v23
	v_and_b32_e32 v214, 15, v213
	v_or_b32_e32 v215, s60, v214
	v_mul_u32_u24_e32 v216, 0x90, v215
	v_and_b32_e32 v217, -16, v213
	v_add3_u32 v141, s54, v216, v217
	v_mov_b32_e32 v213, v23
	v_and_b32_e32 v214, 15, v213
	v_mul_u32_u24_e32 v215, 0x90, v214
	v_add_u32_e32 v216, 0x1200, v215
	v_and_b32_e32 v217, -16, v213
	v_add3_u32 v142, s55, v216, v217
	v_mov_b32_e32 v213, v23
	v_and_b32_e32 v214, 15, v213
	v_mul_u32_u24_e32 v215, 0x90, v214
	v_add_u32_e32 v216, 0x900, v215
	v_and_b32_e32 v217, -16, v213
	v_add3_u32 v143, s55, v216, v217
	v_mov_b32_e32 v213, v23
	v_and_b32_e32 v214, 15, v213
	v_or_b32_e32 v215, 16, v214
	v_mul_u32_u24_e32 v216, 0x90, v215
	v_and_b32_e32 v217, -16, v213
	v_add3_u32 v144, s55, v216, v217
	v_mov_b32_e32 v213, v23
	v_and_b32_e32 v214, 15, v213
	v_or_b32_e32 v215, 32, v214
	v_mul_u32_u24_e32 v216, 0x90, v215
	v_and_b32_e32 v217, -16, v213
	v_add3_u32 v145, s55, v216, v217
	v_mov_b32_e32 v213, v23
	v_and_b32_e32 v214, 15, v213
	v_or_b32_e32 v215, 48, v214
	v_mul_u32_u24_e32 v216, 0x90, v215
	v_and_b32_e32 v217, -16, v213
	v_add3_u32 v146, s55, v216, v217
	v_mov_b32_e32 v213, v23
	v_mul_lo_u32 v214, v213, s76
	v_add_u32_e32 v147, 0, v214
	v_mov_b32_e32 v213, v23
	v_lshlrev_b32_e32 v214, 2, v213
	v_add_u32_e32 v215, 0, v214
	v_add_u32_e32 v148, 0x12000, v215
	v_mov_b32_e32 v213, v23
	v_and_b32_e32 v214, 15, v213
	v_mul_u32_u24_e32 v215, 0x50, v214
	v_and_b32_e32 v216, -16, v213
	v_add3_u32 v217, 0, v215, v216
	v_add_u32_e32 v218, s59, v217
	v_add_u32_e32 v149, 0x14400, v218
	v_mov_b32_e32 v213, v23
	v_and_b32_e32 v214, 15, v213
	v_mul_u32_u24_e32 v215, 0x50, v214
	v_and_b32_e32 v216, -16, v213
	v_add3_u32 v217, 0, v215, v216
	v_add_u32_e32 v218, s59, v217
	v_add_u32_e32 v150, 0x1e800, v218
	v_mov_b32_e32 v213, v23
	v_ashrrev_i32_e32 v214, 4, v213
	v_lshlrev_b32_e32 v215, 3, v214
	v_add_u32_e32 v216, s56, v215
	v_and_b32_e32 v217, 15, v213
	v_or_b32_e32 v218, s57, v217
	v_mul_u32_u24_e32 v219, 0x90, v218
	v_add_u32_e32 v151, v216, v219
	v_mov_b32_e32 v213, v23
	v_ashrrev_i32_e32 v214, 4, v213
	v_lshlrev_b32_e32 v215, 3, v214
	v_add_u32_e32 v216, s56, v215
	v_and_b32_e32 v217, 15, v213
	v_or_b32_e32 v218, s60, v217
	v_mul_u32_u24_e32 v219, 0x90, v218
	v_add_u32_e32 v152, v216, v219
	v_mov_b32_e32 v213, v23
	v_ashrrev_i32_e32 v214, 4, v213
	v_lshlrev_b32_e32 v215, 3, v214
	v_add_u32_e32 v216, s48, v215
	v_add_u32_e32 v217, s58, v216
	v_and_b32_e32 v218, 15, v213
	v_mul_u32_u24_e32 v219, 0x90, v218
	v_add_u32_e32 v220, 0x1200, v219
	v_add_u32_e32 v153, v217, v220
	v_mov_b32_e32 v213, v23
	v_ashrrev_i32_e32 v214, 4, v213
	v_lshlrev_b32_e32 v215, 3, v214
	v_add_u32_e32 v216, s48, v215
	v_add_u32_e32 v217, s58, v216
	v_and_b32_e32 v218, 15, v213
	v_mul_u32_u24_e32 v219, 0x90, v218
	v_add_u32_e32 v220, 0x900, v219
	v_add_u32_e32 v154, v217, v220
	v_mov_b32_e32 v213, v23
	v_ashrrev_i32_e32 v214, 4, v213
	v_lshlrev_b32_e32 v215, 3, v214
	v_add_u32_e32 v216, s48, v215
	v_add_u32_e32 v217, s58, v216
	v_and_b32_e32 v218, 15, v213
	v_mul_u32_u24_e32 v219, 0x90, v218
	v_add_u32_e32 v155, v217, v219
	v_mov_b32_e32 v213, v23
	v_and_b32_e32 v214, 15, v213
	v_mov_b32_e32 v215, s55
	v_mad_u32_u24 v216, v214, s76, v215
	v_and_b32_e32 v217, -16, v213
	v_add_u32_e32 v156, v216, v217
	v_mov_b32_e32 v213, v23
	v_lshlrev_b32_e32 v214, 2, v213
	v_add_u32_e32 v158, s49, v214
	v_mov_b32_e32 v213, v23
	v_mul_lo_u32 v214, v213, s76
	v_add_u32_e32 v159, s53, v214
	v_mov_b32_e32 v213, v23
	v_and_b32_e32 v160, -16, v213
	v_mov_b32_e32 v213, v23
	v_and_b32_e32 v161, 15, v213
	v_mov_b32_e32 v213, v23
	v_ashrrev_i32_e32 v162, 4, v213
	v_mov_b32_e32 v213, v23
	v_ashrrev_i32_e32 v214, 4, v213
	v_lshlrev_b32_e32 v215, 2, v214
	v_add_u32_e32 v216, 16, v215
	v_and_b32_e32 v217, 15, v213
	v_or_b32_e32 v218, s60, v217
	v_cmp_le_i32_e32 vcc, v216, v218
	s_nop 1
	v_cndmask_b32_e64 v219, 0, 1, vcc
	v_cmp_lt_i32_e32 vcc, v216, v218
	s_nop 1
	v_cndmask_b32_e64 v220, 0, 1, vcc
	v_cndmask_b32_e64 v221, v219, v220, s[20:21]
	v_and_b32_e32 v222, 1, v221
	v_cmp_eq_u32_e32 vcc, 1, v222
	s_nop 1
	v_cndmask_b32_e64 v163, 0, -1, vcc
	v_mov_b32_e32 v213, v23
	v_ashrrev_i32_e32 v214, 4, v213
	v_lshlrev_b32_e32 v215, 2, v214
	v_add_u32_e32 v216, 17, v215
	v_and_b32_e32 v217, 15, v213
	v_or_b32_e32 v218, s60, v217
	v_cmp_le_i32_e32 vcc, v216, v218
	s_nop 1
	v_cndmask_b32_e64 v219, 0, 1, vcc
	v_cmp_lt_i32_e32 vcc, v216, v218
	s_nop 1
	v_cndmask_b32_e64 v220, 0, 1, vcc
	v_cndmask_b32_e64 v221, v219, v220, s[20:21]
	v_and_b32_e32 v222, 1, v221
	v_cmp_eq_u32_e32 vcc, 1, v222
	s_nop 1
	v_cndmask_b32_e64 v164, 0, -1, vcc
	v_mov_b32_e32 v213, v23
	v_ashrrev_i32_e32 v214, 4, v213
	v_cmp_gt_i32_e32 vcc, 2, v214
	s_nop 1
	v_cndmask_b32_e64 v165, 0, -1, vcc
	v_mov_b32_e32 v213, v23
	v_and_b32_e32 v214, 15, v213
	v_or_b32_e32 v215, s57, v214
	v_ashrrev_i32_e32 v216, 4, v213
	v_lshlrev_b32_e32 v217, 2, v216
	v_or_b32_e32 v218, v217, v69
	v_cmp_gt_i32_e32 vcc, v215, v218
	s_nop 1
	v_cndmask_b32_e64 v166, 0, -1, vcc
	v_mov_b32_e32 v213, v23
	v_and_b32_e32 v214, 15, v213
	v_or_b32_e32 v215, s60, v214
	v_ashrrev_i32_e32 v216, 4, v213
	v_lshlrev_b32_e32 v217, 2, v216
	v_or_b32_e32 v218, v217, v69
	v_cmp_gt_i32_e32 vcc, v215, v218
	s_nop 1
	v_cndmask_b32_e64 v167, 0, -1, vcc
	v_mov_b32_e32 v213, v23
	v_and_b32_e32 v214, 15, v213
	v_ashrrev_i32_e32 v215, 4, v213
	v_lshlrev_b32_e32 v216, 2, v215
	v_add_u32_e32 v217, s57, v216
	v_cmp_le_i32_e32 vcc, v214, v217
	s_nop 1
	v_cndmask_b32_e64 v168, 0, -1, vcc
	v_mov_b32_e32 v213, v23
	v_and_b32_e32 v214, 15, v213
	v_or_b32_e32 v215, 16, v214
	v_ashrrev_i32_e32 v216, 4, v213
	v_lshlrev_b32_e32 v217, 2, v216
	v_add_u32_e32 v218, s57, v217
	v_cmp_le_i32_e32 vcc, v215, v218
	s_nop 1
	v_cndmask_b32_e64 v169, 0, -1, vcc
	v_mov_b32_e32 v213, v23
	v_and_b32_e32 v214, 15, v213
	v_or_b32_e32 v215, 32, v214
	v_ashrrev_i32_e32 v216, 4, v213
	v_lshlrev_b32_e32 v217, 2, v216
	v_add_u32_e32 v218, s57, v217
	v_cmp_le_i32_e32 vcc, v215, v218
	s_nop 1
	v_cndmask_b32_e64 v170, 0, -1, vcc
	v_mov_b32_e32 v213, v23
	v_and_b32_e32 v214, 15, v213
	v_add_u32_e32 v215, 13, v214
	v_ashrrev_i32_e32 v216, 4, v213
	v_lshlrev_b32_e32 v217, 2, v216
	v_add_u32_e32 v218, s57, v217
	v_cmp_lt_i32_e32 vcc, v215, v218
	s_nop 1
	v_cndmask_b32_e64 v171, 0, -1, vcc
	v_mov_b32_e32 v213, v23
	v_and_b32_e32 v214, 15, v213
	v_add_u32_e32 v215, 14, v214
	v_ashrrev_i32_e32 v216, 4, v213
	v_lshlrev_b32_e32 v217, 2, v216
	v_add_u32_e32 v218, s57, v217
	v_cmp_lt_i32_e32 vcc, v215, v218
	s_nop 1
	v_cndmask_b32_e64 v172, 0, -1, vcc
	v_mov_b32_e32 v213, v23
	v_ashrrev_i32_e32 v214, 4, v213
	v_lshlrev_b32_e32 v215, 2, v214
	v_add_u32_e32 v216, 16, v215
	v_cndmask_b32_e64 v217, 1, 0, s[20:21]
	v_and_b32_e32 v218, 15, v213
	v_or_b32_e32 v219, s57, v218
	v_add_u32_e32 v220, v217, v219
	v_cmp_lt_i32_e32 vcc, v216, v220
	s_nop 1
	v_cndmask_b32_e64 v173, 0, -1, vcc
	v_mov_b32_e32 v213, v23
	v_ashrrev_i32_e32 v214, 4, v213
	v_lshlrev_b32_e32 v215, 2, v214
	v_add_u32_e32 v216, 17, v215
	v_cndmask_b32_e64 v217, 1, 0, s[20:21]
	v_and_b32_e32 v218, 15, v213
	v_or_b32_e32 v219, s57, v218
	v_add_u32_e32 v220, v217, v219
	v_cmp_lt_i32_e32 vcc, v216, v220
	s_nop 1
	v_cndmask_b32_e64 v174, 0, -1, vcc
	v_mov_b32_e32 v213, v23
	v_ashrrev_i32_e32 v214, 4, v213
	v_lshlrev_b32_e32 v215, 2, v214
	v_add_u32_e32 v216, 18, v215
	v_cndmask_b32_e64 v217, 1, 0, s[20:21]
	v_and_b32_e32 v218, 15, v213
	v_or_b32_e32 v219, s57, v218
	v_add_u32_e32 v220, v217, v219
	v_cmp_lt_i32_e32 vcc, v216, v220
	s_nop 1
	v_cndmask_b32_e64 v175, 0, -1, vcc
	v_mov_b32_e32 v213, v23
	v_ashrrev_i32_e32 v214, 4, v213
	v_lshlrev_b32_e32 v215, 2, v214
	v_add_u32_e32 v216, 18, v215
	v_cndmask_b32_e64 v217, 1, 0, s[20:21]
	v_and_b32_e32 v218, 15, v213
	v_or_b32_e32 v219, s60, v218
	v_add_u32_e32 v220, v217, v219
	v_cmp_lt_i32_e32 vcc, v216, v220
	s_nop 1
	v_cndmask_b32_e64 v176, 0, -1, vcc
	v_mov_b32_e32 v213, v23
	v_ashrrev_i32_e32 v214, 4, v213
	v_lshlrev_b32_e32 v215, 2, v214
	v_add_u32_e32 v216, 19, v215
	v_cndmask_b32_e64 v217, 1, 0, s[20:21]
	v_and_b32_e32 v218, 15, v213
	v_or_b32_e32 v219, s57, v218
	v_add_u32_e32 v220, v217, v219
	v_cmp_lt_i32_e32 vcc, v216, v220
	s_nop 1
	v_cndmask_b32_e64 v177, 0, -1, vcc
	v_mov_b32_e32 v213, v23
	v_ashrrev_i32_e32 v214, 4, v213
	v_lshlrev_b32_e32 v215, 2, v214
	v_add_u32_e32 v216, 19, v215
	v_cndmask_b32_e64 v217, 1, 0, s[20:21]
	v_and_b32_e32 v218, 15, v213
	v_or_b32_e32 v219, s60, v218
	v_add_u32_e32 v220, v217, v219
	v_cmp_lt_i32_e32 vcc, v216, v220
	s_nop 1
	v_cndmask_b32_e64 v178, 0, -1, vcc
	v_mov_b32_e32 v213, v23
	v_and_b32_e32 v214, 15, v213
	v_add_u32_e32 v215, 29, v214
	v_ashrrev_i32_e32 v216, 4, v213
	v_lshlrev_b32_e32 v217, 2, v216
	v_add_u32_e32 v218, s57, v217
	v_cmp_lt_i32_e32 vcc, v215, v218
	s_nop 1
	v_cndmask_b32_e64 v179, 0, -1, vcc
	v_mov_b32_e32 v213, v23
	v_and_b32_e32 v214, 15, v213
	v_add_u32_e32 v215, 30, v214
	v_ashrrev_i32_e32 v216, 4, v213
	v_lshlrev_b32_e32 v217, 2, v216
	v_add_u32_e32 v218, s57, v217
	v_cmp_lt_i32_e32 vcc, v215, v218
	s_nop 1
	v_cndmask_b32_e64 v180, 0, -1, vcc
	v_mov_b32_e32 v213, v23
	v_ashrrev_i32_e32 v214, 4, v213
	v_lshlrev_b32_e32 v215, 2, v214
	v_add_u32_e32 v216, 32, v215
	v_cndmask_b32_e64 v217, 1, 0, s[20:21]
	v_and_b32_e32 v218, 15, v213
	v_or_b32_e32 v219, s57, v218
	v_add_u32_e32 v220, v217, v219
	v_cmp_lt_i32_e32 vcc, v216, v220
	s_nop 1
	v_cndmask_b32_e64 v181, 0, -1, vcc
	v_mov_b32_e32 v213, v23
	v_ashrrev_i32_e32 v214, 4, v213
	v_lshlrev_b32_e32 v215, 2, v214
	v_add_u32_e32 v216, 32, v215
	v_cndmask_b32_e64 v217, 1, 0, s[20:21]
	v_and_b32_e32 v218, 15, v213
	v_or_b32_e32 v219, s60, v218
	v_add_u32_e32 v220, v217, v219
	v_cmp_lt_i32_e32 vcc, v216, v220
	s_nop 1
	v_cndmask_b32_e64 v182, 0, -1, vcc
	v_mov_b32_e32 v213, v23
	v_ashrrev_i32_e32 v214, 4, v213
	v_lshlrev_b32_e32 v215, 2, v214
	v_add_u32_e32 v216, 33, v215
	v_cndmask_b32_e64 v217, 1, 0, s[20:21]
	v_and_b32_e32 v218, 15, v213
	v_or_b32_e32 v219, s57, v218
	v_add_u32_e32 v220, v217, v219
	v_cmp_lt_i32_e32 vcc, v216, v220
	s_nop 1
	v_cndmask_b32_e64 v183, 0, -1, vcc
	v_mov_b32_e32 v213, v23
	v_ashrrev_i32_e32 v214, 4, v213
	v_lshlrev_b32_e32 v215, 2, v214
	v_add_u32_e32 v216, 33, v215
	v_cndmask_b32_e64 v217, 1, 0, s[20:21]
	v_and_b32_e32 v218, 15, v213
	v_or_b32_e32 v219, s60, v218
	v_add_u32_e32 v220, v217, v219
	v_cmp_lt_i32_e32 vcc, v216, v220
	s_nop 1
	v_cndmask_b32_e64 v184, 0, -1, vcc
	v_mov_b32_e32 v213, v23
	v_ashrrev_i32_e32 v214, 4, v213
	v_lshlrev_b32_e32 v215, 2, v214
	v_add_u32_e32 v216, 34, v215
	v_cndmask_b32_e64 v217, 1, 0, s[20:21]
	v_and_b32_e32 v218, 15, v213
	v_or_b32_e32 v219, s57, v218
	v_add_u32_e32 v220, v217, v219
	v_cmp_lt_i32_e32 vcc, v216, v220
	s_nop 1
	v_cndmask_b32_e64 v185, 0, -1, vcc
	v_mov_b32_e32 v213, v23
	v_ashrrev_i32_e32 v214, 4, v213
	v_lshlrev_b32_e32 v215, 2, v214
	v_add_u32_e32 v216, 34, v215
	v_cndmask_b32_e64 v217, 1, 0, s[20:21]
	v_and_b32_e32 v218, 15, v213
	v_or_b32_e32 v219, s60, v218
	v_add_u32_e32 v220, v217, v219
	v_cmp_lt_i32_e32 vcc, v216, v220
	s_nop 1
	v_cndmask_b32_e64 v186, 0, -1, vcc
	v_mov_b32_e32 v213, v23
	v_ashrrev_i32_e32 v214, 4, v213
	v_lshlrev_b32_e32 v215, 2, v214
	v_add_u32_e32 v216, 35, v215
	v_cndmask_b32_e64 v217, 1, 0, s[20:21]
	v_and_b32_e32 v218, 15, v213
	v_or_b32_e32 v219, s57, v218
	v_add_u32_e32 v220, v217, v219
	v_cmp_lt_i32_e32 vcc, v216, v220
	s_nop 1
	v_cndmask_b32_e64 v187, 0, -1, vcc
	v_mov_b32_e32 v213, v23
	v_ashrrev_i32_e32 v214, 4, v213
	v_lshlrev_b32_e32 v215, 2, v214
	v_add_u32_e32 v216, 35, v215
	v_cndmask_b32_e64 v217, 1, 0, s[20:21]
	v_and_b32_e32 v218, 15, v213
	v_or_b32_e32 v219, s60, v218
	v_add_u32_e32 v220, v217, v219
	v_cmp_lt_i32_e32 vcc, v216, v220
	s_nop 1
	v_cndmask_b32_e64 v188, 0, -1, vcc
	v_mov_b32_e32 v213, v23
	v_ashrrev_i32_e32 v214, 4, v213
	v_lshlrev_b32_e32 v215, 2, v214
	v_add_u32_e32 v216, 48, v215
	v_cndmask_b32_e64 v217, 1, 0, s[20:21]
	v_and_b32_e32 v218, 15, v213
	v_or_b32_e32 v219, s60, v218
	v_add_u32_e32 v220, v217, v219
	v_cmp_lt_i32_e32 vcc, v216, v220
	s_nop 1
	v_cndmask_b32_e64 v189, 0, -1, vcc
	v_mov_b32_e32 v213, v23
	v_ashrrev_i32_e32 v214, 4, v213
	v_lshlrev_b32_e32 v215, 2, v214
	v_add_u32_e32 v216, 49, v215
	v_cndmask_b32_e64 v217, 1, 0, s[20:21]
	v_and_b32_e32 v218, 15, v213
	v_or_b32_e32 v219, s60, v218
	v_add_u32_e32 v220, v217, v219
	v_cmp_lt_i32_e32 vcc, v216, v220
	s_nop 1
	v_cndmask_b32_e64 v190, 0, -1, vcc
	v_mov_b32_e32 v213, v23
	v_ashrrev_i32_e32 v214, 4, v213
	v_lshlrev_b32_e32 v215, 2, v214
	v_add_u32_e32 v216, 50, v215
	v_cndmask_b32_e64 v217, 1, 0, s[20:21]
	v_and_b32_e32 v218, 15, v213
	v_or_b32_e32 v219, s60, v218
	v_add_u32_e32 v220, v217, v219
	v_cmp_lt_i32_e32 vcc, v216, v220
	s_nop 1
	v_cndmask_b32_e64 v191, 0, -1, vcc
	v_mov_b32_e32 v213, v23
	v_ashrrev_i32_e32 v214, 4, v213
	v_lshlrev_b32_e32 v215, 2, v214
	v_add_u32_e32 v216, 51, v215
	v_cndmask_b32_e64 v217, 1, 0, s[20:21]
	v_and_b32_e32 v218, 15, v213
	v_or_b32_e32 v219, s60, v218
	v_add_u32_e32 v220, v217, v219
	v_cmp_lt_i32_e32 vcc, v216, v220
	s_nop 1
	v_cndmask_b32_e64 v192, 0, -1, vcc
	v_mov_b32_e32 v213, v23
	v_and_b32_e32 v214, 15, v213
	v_ashrrev_i32_e32 v215, 4, v213
	v_lshlrev_b32_e32 v216, 2, v215
	v_add_u32_e32 v217, s57, v216
	v_cmp_lt_i32_e32 vcc, v214, v217
	s_nop 1
	v_cndmask_b32_e64 v193, 0, -1, vcc
	v_mov_b32_e32 v213, v23
	v_and_b32_e32 v214, 15, v213
	v_ashrrev_i32_e32 v215, 4, v213
	v_lshlrev_b32_e32 v216, 2, v215
	v_add_u32_e32 v217, s57, v216
	v_or_b32_e32 v218, 2, v217
	v_cmp_lt_i32_e32 vcc, v214, v218
	s_nop 1
	v_cndmask_b32_e64 v194, 0, -1, vcc
	v_mov_b32_e32 v213, v23
	v_and_b32_e32 v214, 15, v213
	v_ashrrev_i32_e32 v215, 4, v213
	v_lshlrev_b32_e32 v216, 2, v215
	v_add_u32_e32 v217, s57, v216
	v_or_b32_e32 v218, 3, v217
	v_cmp_lt_i32_e32 vcc, v214, v218
	s_nop 1
	v_cndmask_b32_e64 v195, 0, -1, vcc
	v_mov_b32_e32 v213, v23
	v_ashrrev_i32_e32 v214, 4, v213
	v_lshlrev_b32_e32 v215, 2, v214
	v_cndmask_b32_e64 v216, 1, 0, s[20:21]
	v_and_b32_e32 v217, 15, v213
	v_or_b32_e32 v218, s57, v217
	v_add_u32_e32 v219, v216, v218
	v_cmp_lt_i32_e32 vcc, v215, v219
	s_nop 1
	v_cndmask_b32_e64 v196, 0, -1, vcc
	v_mov_b32_e32 v213, v23
	v_ashrrev_i32_e32 v214, 4, v213
	v_lshlrev_b32_e32 v215, 2, v214
	v_cndmask_b32_e64 v216, 1, 0, s[20:21]
	v_and_b32_e32 v217, 15, v213
	v_or_b32_e32 v218, s60, v217
	v_add_u32_e32 v219, v216, v218
	v_cmp_lt_i32_e32 vcc, v215, v219
	s_nop 1
	v_cndmask_b32_e64 v197, 0, -1, vcc
	v_mov_b32_e32 v213, v23
	v_and_b32_e32 v214, 15, v213
	v_or_b32_e32 v215, 16, v214
	v_ashrrev_i32_e32 v216, 4, v213
	v_lshlrev_b32_e32 v217, 2, v216
	v_add_u32_e32 v218, s57, v217
	v_cmp_lt_i32_e32 vcc, v215, v218
	s_nop 1
	v_cndmask_b32_e64 v198, 0, -1, vcc
	v_mov_b32_e32 v213, v23
	v_ashrrev_i32_e32 v214, 4, v213
	v_lshlrev_b32_e32 v215, 2, v214
	v_or_b32_e32 v216, 2, v215
	v_cndmask_b32_e64 v217, 1, 0, s[20:21]
	v_and_b32_e32 v218, 15, v213
	v_or_b32_e32 v219, s57, v218
	v_add_u32_e32 v220, v217, v219
	v_cmp_lt_i32_e32 vcc, v216, v220
	s_nop 1
	v_cndmask_b32_e64 v199, 0, -1, vcc
	v_mov_b32_e32 v213, v23
	v_ashrrev_i32_e32 v214, 4, v213
	v_lshlrev_b32_e32 v215, 2, v214
	v_or_b32_e32 v216, 2, v215
	v_cndmask_b32_e64 v217, 1, 0, s[20:21]
	v_and_b32_e32 v218, 15, v213
	v_or_b32_e32 v219, s60, v218
	v_add_u32_e32 v220, v217, v219
	v_cmp_lt_i32_e32 vcc, v216, v220
	s_nop 1
	v_cndmask_b32_e64 v200, 0, -1, vcc
	v_mov_b32_e32 v213, v23
	v_and_b32_e32 v214, 15, v213
	v_or_b32_e32 v215, 32, v214
	v_ashrrev_i32_e32 v216, 4, v213
	v_lshlrev_b32_e32 v217, 2, v216
	v_add_u32_e32 v218, s57, v217
	v_cmp_lt_i32_e32 vcc, v215, v218
	s_nop 1
	v_cndmask_b32_e64 v201, 0, -1, vcc
	v_mov_b32_e32 v213, v23
	v_ashrrev_i32_e32 v214, 4, v213
	v_lshlrev_b32_e32 v215, 2, v214
	v_or_b32_e32 v216, 3, v215
	v_cndmask_b32_e64 v217, 1, 0, s[20:21]
	v_and_b32_e32 v218, 15, v213
	v_or_b32_e32 v219, s57, v218
	v_add_u32_e32 v220, v217, v219
	v_cmp_lt_i32_e32 vcc, v216, v220
	s_nop 1
	v_cndmask_b32_e64 v202, 0, -1, vcc
	v_mov_b32_e32 v213, v23
	v_ashrrev_i32_e32 v214, 4, v213
	v_lshlrev_b32_e32 v215, 2, v214
	v_or_b32_e32 v216, 3, v215
	v_cndmask_b32_e64 v217, 1, 0, s[20:21]
	v_and_b32_e32 v218, 15, v213
	v_or_b32_e32 v219, s60, v218
	v_add_u32_e32 v220, v217, v219
	v_cmp_lt_i32_e32 vcc, v216, v220
	s_nop 1
	v_cndmask_b32_e64 v203, 0, -1, vcc
	v_mov_b32_e32 v213, v23
	v_lshl_add_u32 v204, v213, 1, s74
	v_mov_b32_e32 v213, v23
	v_ashrrev_i32_e32 v214, 4, v213
	s_movk_i32 s96, 0x500
	v_mul_lo_u32 v215, v214, s96
	v_cmp_gt_i32_e32 vcc, 2, v214
	s_nop 1
	v_cndmask_b32_e32 v216, v80, v81, vcc
	v_add3_u32 v217, 0, v215, v216
	v_mov_b32_e32 v205, v217
	v_mov_b32_e32 v206, s16
	v_mov_b32_e32 v207, v23
	v_mov_b32_e32 v213, v23
	v_and_b32_e32 v214, 15, v213
	v_mul_u32_u24_e32 v208, 0x90, v214
	v_mov_b32_e32 v213, v23
	v_and_b32_e32 v214, 15, v213
	v_or_b32_e32 v209, 16, v214
	v_mov_b32_e32 v213, v23
	v_and_b32_e32 v214, 15, v213
	v_or_b32_e32 v210, 32, v214
	v_mov_b32_e32 v213, v23
	v_and_b32_e32 v214, 15, v213
	v_or_b32_e32 v211, 48, v214
	s_mov_b32 s96, 0x5040100
	s_mov_b32 s97, 0x7060302
	s_branch .LBB0_664

.LBB0_680:
	v_lshlrev_b32_e32 v0, 16, v75
	v_lshlrev_b32_e32 v96, 16, v37
	v_lshlrev_b32_e32 v94, 16, v39
	v_sub_f32_e32 v0, v0, v96
	v_sub_f32_e32 v1, v96, v94
	v_lshlrev_b32_e32 v92, 16, v46
	v_lshlrev_b32_e32 v2, 16, v48
	s_waitcnt vmcnt(9)
	v_fmac_f32_e32 v96, v84, v0
	v_sub_f32_e32 v0, v94, v92
	v_fmac_f32_e32 v94, v1, v84
	v_sub_f32_e32 v1, v92, v2
	v_lshlrev_b32_e32 v4, 16, v27
	v_lshlrev_b32_e32 v5, 16, v43
	v_fmac_f32_e32 v92, v0, v84
	v_fma_f32 v90, v1, v84, v2
	v_lshlrev_b32_e32 v1, 16, v38
	v_lshlrev_b32_e32 v0, 16, v76
	v_lshlrev_b32_e32 v7, 16, v50
	v_mov_b32_e32 v6, v1
	v_pk_add_f32 v[0:1], v[0:1], v[4:5] neg_lo:[0,1] neg_hi:[0,1]
	v_lshlrev_b32_e32 v11, 16, v42
	s_waitcnt vmcnt(8)
	v_pk_fma_f32 v[8:9], v[22:23], v[0:1], v[4:5] op_sel_hi:[0,1,1]
	v_lshlrev_b32_e32 v10, 16, v25
	v_pk_add_f32 v[4:5], v[4:5], v[6:7] neg_lo:[0,1] neg_hi:[0,1]
	v_lshlrev_b32_e32 v95, 16, v55
	v_lshlrev_b32_e32 v93, 16, v62
	v_pk_add_f32 v[0:1], v[10:11], -1.0 op_sel_hi:[1,0]
	v_pk_fma_f32 v[14:15], v[4:5], v[22:23], v[6:7] op_sel_hi:[1,0,1]
	v_sub_f32_e32 v2, v2, v95
	v_sub_f32_e32 v6, v95, v93
	v_lshlrev_b32_e32 v91, 16, v64
	v_lshlrev_b32_e32 v89, 16, v72
	s_waitcnt vmcnt(6)
	v_mul_f32_e32 v97, v85, v8
	s_waitcnt vmcnt(5)
	v_pk_fma_f32 v[0:1], v[0:1], v[26:27], 1.0 op_sel_hi:[1,0,0]
	v_lshlrev_b32_e32 v18, 16, v59
	v_fmac_f32_e32 v95, v2, v84
	v_sub_f32_e32 v2, v93, v91
	v_fmac_f32_e32 v93, v6, v84
	v_lshlrev_b32_e32 v19, 16, v70
	v_sub_f32_e32 v6, v91, v89
	v_lshlrev_b32_e32 v12, 16, v40
	v_lshlrev_b32_e32 v13, 16, v49
	v_mul_f32_e32 v29, v97, v97
	v_pk_mul_f32 v[0:1], v[8:9], v[0:1]
	v_mul_f32_e32 v98, v85, v14
	v_mul_f32_e32 v99, v85, v9
	v_lshlrev_b32_e32 v8, 16, v53
	v_lshlrev_b32_e32 v9, 16, v65
	v_fmac_f32_e32 v89, v6, v84
	v_pk_mov_b32 v[6:7], v[6:7], v[18:19] op_sel:[1,0]
	v_mul_f32_e32 v34, v98, v98
	v_pk_add_f32 v[4:5], v[12:13], -1.0 op_sel_hi:[1,0]
	v_pk_add_f32 v[6:7], v[6:7], v[8:9] neg_lo:[0,1] neg_hi:[0,1]
	v_add_f32_dpp v119, v29, v29 quad_perm:[1,0,3,2] row_mask:0xf bank_mask:0xf
	v_pk_fma_f32 v[4:5], v[4:5], v[26:27], 1.0 op_sel_hi:[1,0,0]
	v_mul_f32_e32 v102, v99, v99
	v_mul_f32_e32 v100, v85, v15
	v_pk_fma_f32 v[30:31], v[6:7], v[22:23], v[8:9] op_sel_hi:[1,0,1]
	v_pk_add_f32 v[8:9], v[8:9], v[18:19] neg_lo:[0,1] neg_hi:[0,1]
	v_add_f32_dpp v29, v34, v34 quad_perm:[1,0,3,2] row_mask:0xf bank_mask:0xf
	v_pk_mul_f32 v[4:5], v[14:15], v[4:5]
	v_mul_f32_e32 v106, v100, v100
	v_mul_f32_e32 v104, v85, v30
	v_lshlrev_b32_e32 v15, 16, v67
	v_lshlrev_b32_e32 v14, 16, v58
	v_pk_fma_f32 v[18:19], v[8:9], v[22:23], v[18:19] op_sel_hi:[1,0,1]
	v_add_f32_dpp v34, v102, v102 quad_perm:[1,0,3,2] row_mask:0xf bank_mask:0xf
	v_lshlrev_b32_e32 v16, 16, v60
	v_lshlrev_b32_e32 v17, 16, v73
	v_fmac_f32_e32 v91, v2, v84
	v_mul_f32_e32 v2, v104, v104
	v_pk_add_f32 v[6:7], v[14:15], -1.0 op_sel_hi:[1,0]
	v_mul_f32_e32 v110, v85, v18
	v_add_f32_dpp v102, v106, v106 quad_perm:[1,0,3,2] row_mask:0xf bank_mask:0xf
	v_pk_fma_f32 v[6:7], v[6:7], v[26:27], 1.0 op_sel_hi:[1,0,0]
	v_mul_f32_e32 v113, v110, v110
	v_pk_add_f32 v[8:9], v[16:17], -1.0 op_sel_hi:[1,0]
	v_mul_f32_e32 v111, v85, v31
	v_add_f32_dpp v106, v2, v2 quad_perm:[1,0,3,2] row_mask:0xf bank_mask:0xf
	v_pk_mul_f32 v[6:7], v[30:31], v[6:7]
	v_pk_fma_f32 v[8:9], v[8:9], v[26:27], 1.0 op_sel_hi:[1,0,0]
	v_mul_f32_e32 v31, v111, v111
	v_mul_f32_e32 v112, v85, v19
	v_add_f32_dpp v2, v113, v113 quad_perm:[1,0,3,2] row_mask:0xf bank_mask:0xf
	v_mul_f32_e32 v32, v96, v0
	v_pk_mul_f32 v[8:9], v[18:19], v[8:9]
	v_mul_f32_e32 v19, v112, v112
	v_add_f32_dpp v113, v31, v31 quad_perm:[1,0,3,2] row_mask:0xf bank_mask:0xf
	s_waitcnt vmcnt(4)
	v_mul_f32_e32 v33, v86, v32
	v_mul_f32_e32 v35, v94, v4
	v_add_f32_dpp v31, v19, v19 quad_perm:[1,0,3,2] row_mask:0xf bank_mask:0xf
	v_mul_f32_e32 v101, v86, v35
	v_mul_f32_e32 v30, v95, v6
	v_add_f32_dpp v19, v33, v33 quad_perm:[1,0,3,2] row_mask:0xf bank_mask:0xf
	v_mul_f32_e32 v109, v86, v30
	v_mul_f32_e32 v18, v93, v8
	v_add_f32_dpp v32, v101, v101 quad_perm:[1,0,3,2] row_mask:0xf bank_mask:0xf
	v_mul_f32_e32 v114, v86, v18
	v_mul_f32_e32 v115, v91, v7
	v_add_f32_dpp v101, v109, v109 quad_perm:[1,0,3,2] row_mask:0xf bank_mask:0xf
	v_mul_f32_e32 v116, v86, v115
	v_mul_f32_e32 v103, v92, v1
	v_add_f32_dpp v30, v114, v114 quad_perm:[1,0,3,2] row_mask:0xf bank_mask:0xf
	v_mul_f32_e32 v105, v86, v103
	v_add_f32_dpp v18, v116, v116 quad_perm:[1,0,3,2] row_mask:0xf bank_mask:0xf
	s_nop 0
	v_add_f32_dpp v33, v105, v105 quad_perm:[1,0,3,2] row_mask:0xf bank_mask:0xf
	v_add_f32_dpp v105, v119, v119 quad_perm:[2,3,0,1] row_mask:0xf bank_mask:0xf bound_ctrl:1
	v_add_f32_dpp v18, v18, v18 quad_perm:[2,3,0,1] row_mask:0xf bank_mask:0xf bound_ctrl:1
	v_add_f32_dpp v29, v29, v29 quad_perm:[2,3,0,1] row_mask:0xf bank_mask:0xf bound_ctrl:1
	v_add_f32_dpp v105, v105, v105 row_shr:4 row_mask:0xf bank_mask:0xf bound_ctrl:1
	v_add_f32_dpp v18, v18, v18 row_shr:4 row_mask:0xf bank_mask:0xf bound_ctrl:1
	v_mul_f32_e32 v107, v90, v5
	v_add_f32_dpp v105, v105, v105 row_shr:8 row_mask:0xf bank_mask:0xf bound_ctrl:1
	v_add_f32_dpp v116, v18, v18 row_shr:8 row_mask:0xf bank_mask:0xf bound_ctrl:1
	v_add_f32_dpp v29, v29, v29 row_shr:4 row_mask:0xf bank_mask:0xf bound_ctrl:1
	v_mul_f32_e32 v108, v86, v107
	v_add_f32_dpp v34, v34, v34 quad_perm:[2,3,0,1] row_mask:0xf bank_mask:0xf bound_ctrl:1
	v_add_f32_dpp v29, v29, v29 row_shr:8 row_mask:0xf bank_mask:0xf bound_ctrl:1
	v_add_f32_dpp v105, v105, v105 row_bcast:15 row_mask:0xa bank_mask:0xf
	v_add_f32_dpp v34, v34, v34 row_shr:4 row_mask:0xf bank_mask:0xf bound_ctrl:1
	v_add_f32_dpp v35, v108, v108 quad_perm:[1,0,3,2] row_mask:0xf bank_mask:0xf
	v_add_f32_dpp v102, v102, v102 quad_perm:[2,3,0,1] row_mask:0xf bank_mask:0xf bound_ctrl:1
	v_add_f32_dpp v106, v106, v106 quad_perm:[2,3,0,1] row_mask:0xf bank_mask:0xf bound_ctrl:1
	v_add_f32_dpp v107, v113, v113 quad_perm:[2,3,0,1] row_mask:0xf bank_mask:0xf bound_ctrl:1
	v_add_f32_dpp v34, v34, v34 row_shr:8 row_mask:0xf bank_mask:0xf bound_ctrl:1
	v_add_f32_dpp v113, v29, v29 row_bcast:15 row_mask:0xa bank_mask:0xf
	v_add_f32_dpp v102, v102, v102 row_shr:4 row_mask:0xf bank_mask:0xf bound_ctrl:1
	v_add_f32_dpp v106, v106, v106 row_shr:4 row_mask:0xf bank_mask:0xf bound_ctrl:1
	v_add_f32_dpp v101, v101, v101 quad_perm:[2,3,0,1] row_mask:0xf bank_mask:0xf bound_ctrl:1
	v_add_f32_dpp v102, v102, v102 row_shr:8 row_mask:0xf bank_mask:0xf bound_ctrl:1
	v_add_f32_dpp v108, v106, v106 row_shr:8 row_mask:0xf bank_mask:0xf bound_ctrl:1
	v_add_f32_dpp v106, v34, v34 row_bcast:15 row_mask:0xa bank_mask:0xf
	v_add_f32_dpp v101, v101, v101 row_shr:4 row_mask:0xf bank_mask:0xf bound_ctrl:1
	s_nop 0
	v_add_f32_dpp v2, v2, v2 quad_perm:[2,3,0,1] row_mask:0xf bank_mask:0xf bound_ctrl:1
	v_add_f32_dpp v32, v32, v32 quad_perm:[2,3,0,1] row_mask:0xf bank_mask:0xf bound_ctrl:1
	v_add_f32_dpp v115, v101, v101 row_shr:8 row_mask:0xf bank_mask:0xf bound_ctrl:1
	v_add_f32_dpp v101, v102, v102 row_bcast:15 row_mask:0xa bank_mask:0xf
	v_add_f32_dpp v2, v2, v2 row_shr:4 row_mask:0xf bank_mask:0xf bound_ctrl:1
	v_add_f32_dpp v32, v32, v32 row_shr:4 row_mask:0xf bank_mask:0xf bound_ctrl:1
	s_nop 0
	v_add_f32_dpp v2, v2, v2 row_shr:8 row_mask:0xf bank_mask:0xf bound_ctrl:1
	v_add_f32_dpp v109, v32, v32 row_shr:8 row_mask:0xf bank_mask:0xf bound_ctrl:1
	v_add_f32_dpp v32, v108, v108 row_bcast:15 row_mask:0xa bank_mask:0xf
	v_add_f32_dpp v107, v107, v107 row_shr:4 row_mask:0xf bank_mask:0xf bound_ctrl:1
	s_nop 0
	v_add_f32_dpp v31, v31, v31 quad_perm:[2,3,0,1] row_mask:0xf bank_mask:0xf bound_ctrl:1
	v_add_f32_dpp v107, v107, v107 row_shr:8 row_mask:0xf bank_mask:0xf bound_ctrl:1
	v_add_f32_dpp v29, v2, v2 row_bcast:15 row_mask:0xa bank_mask:0xf
	v_add_f32_dpp v31, v31, v31 row_shr:4 row_mask:0xf bank_mask:0xf bound_ctrl:1
	v_add_f32_dpp v19, v19, v19 quad_perm:[2,3,0,1] row_mask:0xf bank_mask:0xf bound_ctrl:1
	s_nop 0
	v_add_f32_dpp v31, v31, v31 row_shr:8 row_mask:0xf bank_mask:0xf bound_ctrl:1
	v_add_f32_dpp v18, v107, v107 row_bcast:15 row_mask:0xa bank_mask:0xf
	v_add_f32_dpp v19, v19, v19 row_shr:4 row_mask:0xf bank_mask:0xf bound_ctrl:1
	v_mul_f32_e32 v117, v89, v9
	s_nop 0
	v_add_f32_dpp v19, v19, v19 row_shr:8 row_mask:0xf bank_mask:0xf bound_ctrl:1
	v_add_f32_dpp v2, v31, v31 row_bcast:15 row_mask:0xa bank_mask:0xf
	v_mul_f32_e32 v118, v86, v117
	s_nop 0
	v_add_f32_dpp v33, v33, v33 quad_perm:[2,3,0,1] row_mask:0xf bank_mask:0xf bound_ctrl:1
	v_add_f32_dpp v34, v19, v19 row_bcast:15 row_mask:0xa bank_mask:0xf
	s_nop 0
	v_add_f32_dpp v33, v33, v33 row_shr:4 row_mask:0xf bank_mask:0xf bound_ctrl:1
	v_add_f32_dpp v103, v118, v118 quad_perm:[1,0,3,2] row_mask:0xf bank_mask:0xf
	v_add_f32_dpp v35, v35, v35 quad_perm:[2,3,0,1] row_mask:0xf bank_mask:0xf bound_ctrl:1
	v_add_f32_dpp v33, v33, v33 row_shr:8 row_mask:0xf bank_mask:0xf bound_ctrl:1
	v_add_f32_dpp v117, v109, v109 row_bcast:15 row_mask:0xa bank_mask:0xf
	v_add_f32_dpp v35, v35, v35 row_shr:4 row_mask:0xf bank_mask:0xf bound_ctrl:1
	v_add_f32_dpp v30, v30, v30 quad_perm:[2,3,0,1] row_mask:0xf bank_mask:0xf bound_ctrl:1
	s_nop 0
	v_add_f32_dpp v35, v35, v35 row_shr:8 row_mask:0xf bank_mask:0xf bound_ctrl:1
	v_add_f32_dpp v114, v33, v33 row_bcast:15 row_mask:0xa bank_mask:0xf
	v_add_f32_dpp v30, v30, v30 row_shr:4 row_mask:0xf bank_mask:0xf bound_ctrl:1
	s_ashr_i32 s0, s44, 11
	v_add_f32_dpp v107, v35, v35 row_bcast:15 row_mask:0xa bank_mask:0xf
	v_add_f32_dpp v30, v30, v30 row_shr:8 row_mask:0xf bank_mask:0xf bound_ctrl:1
	s_lshl_b32 s4, s44, 6
	v_add_f32_dpp v102, v115, v115 row_bcast:15 row_mask:0xa bank_mask:0xf
	v_add_f32_dpp v103, v103, v103 quad_perm:[2,3,0,1] row_mask:0xf bank_mask:0xf bound_ctrl:1
	s_ashr_i32 s1, s0, 31
	v_add_f32_dpp v33, v30, v30 row_bcast:15 row_mask:0xa bank_mask:0xf
	s_and_b32 s4, s4, 0x1fc0
	v_add_f32_dpp v103, v103, v103 row_shr:4 row_mask:0xf bank_mask:0xf bound_ctrl:1
	s_lshl_b64 s[0:1], s[0:1], 13
	s_nop 0
	v_add_f32_dpp v103, v103, v103 row_shr:8 row_mask:0xf bank_mask:0xf bound_ctrl:1
	v_add_f32_dpp v30, v116, v116 row_bcast:15 row_mask:0xa bank_mask:0xf
	s_add_i32 s4, s4, s33
	s_add_u32 s0, s0, s4
	v_add_f32_dpp v19, v103, v103 row_bcast:15 row_mask:0xa bank_mask:0xf
	s_addc_u32 s1, s1, 0
	s_lshr_b32 s4, s44, 5
	s_and_b32 s4, s4, 60
	v_readlane_b32 s6, v233, 36
	v_mov_b32_e32 v28, v23
	v_add_f32_dpp v123, v105, v105 row_bcast:31 row_mask:0xc bank_mask:0xf
	v_mov_b32_e32 v121, 0
	v_mov_b32_e32 v119, 0
	v_mov_b32_e32 v116, 0
	v_mov_b32_e32 v109, 0
	v_mov_b32_e32 v105, 0
	v_mov_b32_e32 v35, 0
	v_mov_b32_e32 v31, 0
	v_add_f32_dpp v126, v34, v34 row_bcast:31 row_mask:0xc bank_mask:0xf
	v_mov_b32_e32 v122, 0
	v_mov_b32_e32 v120, 0
	v_mov_b32_e32 v118, 0
	v_mov_b32_e32 v115, 0
	v_mov_b32_e32 v108, 0
	v_mov_b32_e32 v103, 0
	v_mov_b32_e32 v34, 0
	v_readlane_b32 s7, v233, 37
	s_add_u32 s22, s6, s4
	v_mov_b32_dpp v121, v113 row_bcast:31 row_mask:0xc bank_mask:0xf
	v_mov_b32_dpp v119, v106 row_bcast:31 row_mask:0xc bank_mask:0xf
	v_mov_b32_dpp v116, v101 row_bcast:31 row_mask:0xc bank_mask:0xf
	v_mov_b32_dpp v109, v32 row_bcast:31 row_mask:0xc bank_mask:0xf
	v_mov_b32_dpp v105, v29 row_bcast:31 row_mask:0xc bank_mask:0xf
	v_mov_b32_dpp v35, v18 row_bcast:31 row_mask:0xc bank_mask:0xf
	v_mov_b32_dpp v31, v2 row_bcast:31 row_mask:0xc bank_mask:0xf
	v_mov_b32_dpp v122, v117 row_bcast:31 row_mask:0xc bank_mask:0xf
	v_mov_b32_dpp v120, v114 row_bcast:31 row_mask:0xc bank_mask:0xf
	v_mov_b32_dpp v118, v107 row_bcast:31 row_mask:0xc bank_mask:0xf
	v_mov_b32_dpp v115, v102 row_bcast:31 row_mask:0xc bank_mask:0xf
	v_mov_b32_dpp v108, v33 row_bcast:31 row_mask:0xc bank_mask:0xf
	v_mov_b32_dpp v103, v30 row_bcast:31 row_mask:0xc bank_mask:0xf
	v_mov_b32_dpp v34, v19 row_bcast:31 row_mask:0xc bank_mask:0xf
	v_cmp_eq_u32_e32 vcc, 0, v28
	s_addc_u32 s23, s7, 0
	v_readlane_b32 s6, v123, 63
	v_readlane_b32 s7, v126, 63
	s_and_saveexec_b64 s[4:5], vcc
	s_cbranch_execz .LBB0_682
	s_lshl_b64 s[8:9], s[0:1], 6
	s_add_u32 s8, s22, s8
	s_addc_u32 s9, s23, s9
	v_mov_b32_e32 v123, s7
	global_store_dword v3, v123, s[8:9]

.LBB0_698:
	v_cndmask_b32_e64 v29, v34, 0, s[24:25]
	v_readlane_b32 s80, v233, 39
	v_add_f32_e32 v34, v35, v29
	v_readlane_b32 s81, v233, 40
	v_readlane_b32 s0, v233, 41
	v_readlane_b32 s1, v233, 42
	v_cndmask_b32_e64 v29, v29, v34, s[80:81]
	v_add_f32_e32 v32, v32, v29
	v_cndmask_b32_e64 v29, v29, v32, s[0:1]
	v_readlane_b32 s0, v233, 43
	v_add_f32_e32 v32, v33, v29
	v_readlane_b32 s1, v233, 44
	s_nop 1
	v_cndmask_b32_e64 v29, v29, v32, s[0:1]
	v_readlane_b32 s0, v233, 45
	v_add_f32_e32 v30, v30, v29
	v_readlane_b32 s1, v233, 46
	s_nop 0
	s_nop 0
	v_cndmask_b32_e64 v29, v29, v30, s[0:1]
	v_readlane_b32 s0, v233, 47
	v_add_f32_e32 v31, v31, v29
	v_readlane_b32 s1, v233, 48
	s_nop 1
	v_cndmask_b32_e64 v29, v29, v31, s[0:1]
	v_add_f32_e32 v18, v18, v29
	s_nop 1
	s_nop 0
	v_readlane_b32 s0, v233, 49
	v_readlane_b32 s1, v233, 50
	s_nop 1
	v_cndmask_b32_e64 v18, v29, v18, s[0:1]
	v_readlane_b32 s0, v233, 51
	v_add_f32_e32 v19, v19, v18
	v_readlane_b32 s1, v233, 52
	s_nop 1
	v_cndmask_b32_e64 v18, v18, v19, s[0:1]
	v_sqrt_f32_e32 v19, s46
	s_nop 0
	v_max_f32_e32 v19, 0x2b8cbccc, v19
	v_rcp_f32_e32 v19, v19
	s_nop 0
	v_mul_f32_e32 v19, v112, v19
	v_add_f32_e32 v109, v109, v18
	v_mul_f32_e32 v17, v19, v17
	v_sqrt_f32_e32 v29, s19
	s_nop 0
	v_max_f32_e32 v29, 0x2b8cbccc, v29
	v_rcp_f32_e32 v29, v29
	s_nop 0
	v_mul_f32_e32 v29, v111, v29
	v_mul_f32_e32 v15, v29, v15
	s_nop 0
	v_sqrt_f32_e32 v30, s18
	s_nop 0
	v_max_f32_e32 v30, 0x2b8cbccc, v30
	v_rcp_f32_e32 v30, v30
	s_nop 0
	v_mul_f32_e32 v114, v110, v30
	v_mul_f32_e32 v16, v114, v16
	s_nop 0
	v_sqrt_f32_e32 v30, s17
	s_nop 0
	v_max_f32_e32 v30, 0x2b8cbccc, v30
	v_rcp_f32_e32 v30, v30
	s_nop 0
	v_mul_f32_e32 v104, v104, v30
	v_mul_f32_e32 v14, v104, v14
	s_nop 0
	v_sqrt_f32_e32 v30, s9
	s_nop 0
	v_max_f32_e32 v30, 0x2b8cbccc, v30
	v_rcp_f32_e32 v30, v30
	s_nop 0
	v_mul_f32_e32 v100, v100, v30
	v_mul_f32_e32 v13, v100, v13
	s_nop 0
	v_sqrt_f32_e32 v30, s8
	s_nop 0
	v_max_f32_e32 v30, 0x2b8cbccc, v30
	v_rcp_f32_e32 v30, v30
	s_nop 0
	v_mul_f32_e32 v115, v99, v30
	v_lshlrev_b32_e32 v110, 16, v61
	v_mov_b32_e32 v111, s6
	v_mul_f32_e32 v11, v115, v11
	s_nop 0
	v_and_b32_e32 v31, 0xffff0000, v88
	v_sqrt_f32_e32 v30, s7
	s_nop 0
	v_max_f32_e32 v30, 0x2b8cbccc, v30
	v_rcp_f32_e32 v30, v30
	s_nop 0
	v_mul_f32_e32 v116, v98, v30
	v_lshlrev_b32_e32 v30, 16, v88
	v_lshlrev_b32_e32 v33, 16, v54
	v_lshlrev_b32_e32 v35, 16, v52
	v_lshlrev_b32_e32 v34, 16, v45
	v_mov_b32_e32 v32, v31
	v_pk_add_f32 v[30:31], v[30:31], v[34:35] neg_lo:[0,1] neg_hi:[0,1]
	v_pk_add_f32 v[98:99], v[34:35], v[32:33] neg_lo:[0,1] neg_hi:[0,1]
	v_pk_fma_f32 v[30:31], v[24:25], v[30:31], v[34:35] op_sel_hi:[0,1,1]
	v_pk_fma_f32 v[34:35], v[98:99], v[24:25], v[32:33] op_sel_hi:[1,0,1]
	v_mul_f32_e32 v32, s6, v79
	v_cmp_lt_f32_e32 vcc, s6, v78
	v_lshlrev_b32_e32 v99, 16, v66
	v_lshlrev_b32_e32 v98, 16, v56
	v_cndmask_b32_e32 v112, v111, v32, vcc
	v_sqrt_f32_e32 v113, v112
	v_lshlrev_b32_e32 v111, 16, v71
	v_pk_mov_b32 v[32:33], v[32:33], v[110:111] op_sel:[1,0]
	v_mul_f32_e32 v12, v116, v12
	v_add_u32_e32 v117, -1, v113
	v_fma_f32 v118, -v117, v113, v112
	v_cmp_ge_f32_e64 s[0:1], 0, v118
	v_add_u32_e32 v118, 1, v113
	v_pk_add_f32 v[32:33], v[32:33], v[98:99] neg_lo:[0,1] neg_hi:[0,1]
	v_cndmask_b32_e64 v117, v113, v117, s[0:1]
	v_fma_f32 v113, -v118, v113, v112
	v_cmp_lt_f32_e64 s[0:1], 0, v113
	v_pk_fma_f32 v[32:33], v[32:33], v[24:25], v[98:99] op_sel_hi:[1,0,1]
	s_nop 0
	v_cndmask_b32_e64 v113, v117, v118, s[0:1]
	v_mul_f32_e32 v117, 0x37800000, v113
	v_cndmask_b32_e32 v113, v113, v117, vcc
	v_cmp_class_f32_e32 vcc, v112, v77
	s_nop 1
	v_cndmask_b32_e32 v112, v113, v112, vcc
	v_max_f32_e32 v117, 0x2b8cbccc, v112
	v_div_scale_f32 v118, s[0:1], v117, v117, v97
	v_pk_add_f32 v[112:113], v[98:99], v[110:111] neg_lo:[0,1] neg_hi:[0,1]
	s_nop 0
	v_pk_fma_f32 v[98:99], v[112:113], v[24:25], v[110:111] op_sel_hi:[1,0,1]
	v_sqrt_f32_e32 v110, s6
	s_nop 0
	v_max_f32_e32 v110, 0x2b8cbccc, v110
	v_rcp_f32_e32 v110, v110
	s_nop 0
	v_mul_f32_e32 v97, v97, v110
	v_mul_f32_e32 v110, 0x3fb8aa3b, v18
	v_exp_f32_e32 v111, v110
	v_mul_f32_e32 v110, 0x3fb8aa3b, v109
	v_exp_f32_e32 v112, v110
	v_mul_f32_e32 v109, 0xbfb8aa3b, v109
	v_exp_f32_e32 v110, v109
	v_mul_f32_e32 v10, v97, v10
	v_mul_f32_e64 v97, v111, -v97
	v_mul_f32_e32 v96, v96, v112
	v_cvt_pk_bf16_f32 v109, v97, s0
	v_cvt_pk_bf16_f32 v96, v96, s0
	v_mul_f32_e32 v97, v10, v110
	v_mul_f32_e32 v111, v0, v110
	v_cvt_pk_bf16_f32 v113, v30, v31
	v_add_f32_e32 v31, v108, v18
	v_cvt_pk_bf16_f32 v97, v97, s0
	v_cvt_pk_bf16_f32 v111, v111, s0
	ds_write_b16 v204, v109
	ds_write_b16 v204, v96 offset:9216
	ds_write_b16 v204, v97 offset:18432
	ds_write_b16 v204, v111 offset:27648
	v_mul_f32_e32 v96, 0x3fb8aa3b, v31
	v_mul_f32_e32 v31, 0xbfb8aa3b, v31
	v_exp_f32_e32 v97, v96
	v_exp_f32_e32 v96, v31
	v_mul_f32_e64 v31, v112, -v116
	v_cvt_pk_bf16_f32 v112, v34, v35
	v_add_f32_e32 v34, v107, v18
	v_mul_f32_e32 v111, v4, v96
	v_mul_f32_e32 v35, 0x3fb8aa3b, v34
	v_cvt_pk_bf16_f32 v31, v31, s0
	v_mul_f32_e32 v94, v94, v97
	v_mul_f32_e32 v108, v12, v96
	v_cvt_pk_bf16_f32 v111, v111, s0
	v_exp_f32_e32 v35, v35
	v_mul_f32_e32 v34, 0xbfb8aa3b, v34
	v_cvt_pk_bf16_f32 v94, v94, s0
	v_cvt_pk_bf16_f32 v108, v108, s0
	ds_write_b16 v204, v31 offset:144
	ds_write_b16 v204, v94 offset:9360
	ds_write_b16 v204, v108 offset:18576
	ds_write_b16 v204, v111 offset:27792
	v_exp_f32_e32 v111, v34
	v_mul_f32_e64 v34, v97, -v115
	v_cvt_pk_bf16_f32 v94, v34, s0
	v_mul_f32_e32 v34, v92, v35
	v_cvt_pk_bf16_f32 v34, v34, s0
	v_mul_f32_e32 v92, v11, v111
	v_mul_f32_e32 v97, v1, v111
	v_cvt_pk_bf16_f32 v92, v92, s0
	v_cvt_pk_bf16_f32 v97, v97, s0
	ds_write_b16 v204, v94 offset:288
	ds_write_b16 v204, v34 offset:9504
	ds_write_b16 v204, v92 offset:18720
	ds_write_b16 v204, v97 offset:27936
	v_add_f32_e32 v34, v106, v18
	v_mul_f32_e32 v92, 0x3fb8aa3b, v34
	v_exp_f32_e32 v92, v92
	v_mul_f32_e32 v34, 0xbfb8aa3b, v34
	v_exp_f32_e32 v97, v34
	v_mul_f32_e64 v34, v35, -v100
	v_cvt_pk_bf16_f32 v100, v34, s0
	v_mul_f32_e32 v34, v90, v92
	v_cvt_pk_bf16_f32 v34, v34, s0
	v_mul_f32_e32 v35, v13, v97
	v_mul_f32_e32 v90, v5, v97
	v_cvt_pk_bf16_f32 v35, v35, s0
	v_cvt_pk_bf16_f32 v90, v90, s0
	ds_write_b16 v204, v100 offset:432
	ds_write_b16 v204, v34 offset:9648
	ds_write_b16 v204, v35 offset:18864
	ds_write_b16 v204, v90 offset:28080
	v_add_f32_e32 v34, v105, v18
	v_mul_f32_e32 v35, 0x3fb8aa3b, v34
	v_exp_f32_e32 v35, v35
	v_mul_f32_e32 v34, 0xbfb8aa3b, v34
	v_exp_f32_e32 v34, v34
	v_mul_f32_e64 v90, v92, -v104
	v_cvt_pk_bf16_f32 v105, v32, v33
	v_add_f32_e32 v32, v103, v18
	v_cvt_pk_bf16_f32 v92, v90, s0
	v_mul_f32_e32 v90, v95, v35
	v_mul_f32_e32 v33, 0x3fb8aa3b, v32
	v_cvt_pk_bf16_f32 v90, v90, s0
	v_mul_f32_e32 v95, v14, v34
	v_mul_f32_e32 v104, v6, v34
	v_exp_f32_e32 v33, v33
	v_mul_f32_e32 v32, 0xbfb8aa3b, v32
	v_cvt_pk_bf16_f32 v95, v95, s0
	v_cvt_pk_bf16_f32 v104, v104, s0
	ds_write_b16 v204, v92 offset:576
	ds_write_b16 v204, v90 offset:9792
	ds_write_b16 v204, v95 offset:19008
	ds_write_b16 v204, v104 offset:28224
	v_exp_f32_e32 v90, v32
	v_mul_f32_e64 v32, v35, -v114
	v_mul_f32_e32 v35, v93, v33
	v_cvt_pk_bf16_f32 v32, v32, s0
	v_cvt_pk_bf16_f32 v35, v35, s0
	v_mul_f32_e32 v93, v16, v90
	v_mul_f32_e32 v95, v8, v90
	v_cvt_pk_bf16_f32 v93, v93, s0
	v_cvt_pk_bf16_f32 v95, v95, s0
	ds_write_b16 v204, v32 offset:720
	ds_write_b16 v204, v35 offset:9936
	ds_write_b16 v204, v93 offset:19152
	ds_write_b16 v204, v95 offset:28368
	v_add_f32_e32 v35, v102, v18
	v_mul_f32_e32 v93, 0x3fb8aa3b, v35
	v_exp_f32_e32 v93, v93
	v_mul_f32_e32 v35, 0xbfb8aa3b, v35
	v_exp_f32_e32 v35, v35
	v_mul_f32_e64 v29, v33, -v29
	v_mul_f32_e32 v33, v91, v93
	v_cvt_pk_bf16_f32 v29, v29, s0
	v_cvt_pk_bf16_f32 v33, v33, s0
	v_mul_f32_e32 v91, v15, v35
	v_mul_f32_e32 v95, v7, v35
	v_add_f32_e32 v18, v101, v18
	v_cvt_pk_bf16_f32 v91, v91, s0
	v_cvt_pk_bf16_f32 v95, v95, s0
	ds_write_b16 v204, v29 offset:864
	ds_write_b16 v204, v33 offset:10080
	ds_write_b16 v204, v91 offset:19296
	ds_write_b16 v204, v95 offset:28512
	v_mul_f32_e32 v33, 0x3fb8aa3b, v18
	v_exp_f32_e32 v33, v33
	v_mul_f32_e32 v18, 0xbfb8aa3b, v18
	v_exp_f32_e32 v91, v18
	v_mul_f32_e64 v18, v93, -v19
	v_mul_f32_e32 v19, v89, v33
	v_cvt_pk_bf16_f32 v18, v18, s0
	v_cvt_pk_bf16_f32 v19, v19, s0
	v_mul_f32_e32 v33, v17, v91
	v_mul_f32_e32 v89, v9, v91
	v_cvt_pk_bf16_f32 v33, v33, s0
	v_cvt_pk_bf16_f32 v89, v89, s0
	ds_write_b16 v204, v18 offset:1008
	ds_write_b16 v204, v19 offset:10224
	ds_write_b16 v204, v33 offset:19440
	ds_write_b16 v204, v89 offset:28656
	v_perm_b32 v30, v31, v109, s96
	v_perm_b32 v31, v100, v94, s96
	v_perm_b32 v33, v18, v29, s96
	v_perm_b32 v32, v32, v92, s96
	v_pk_mul_f32 v[18:19], v[2:3], v[110:111] op_sel_hi:[0,1]
	ds_write_b128 v159, v[30:33] offset:36864
	v_pk_mul_f32 v[30:31], v[2:3], v[96:97] op_sel_hi:[0,1]
	v_pk_mul_f32 v[10:11], v[10:11], v[18:19]
	v_pk_mul_f32 v[0:1], v[0:1], v[18:19]
	v_cvt_pk_bf16_f32 v32, v10, v11
	v_pk_mul_f32 v[10:11], v[12:13], v[30:31]
	v_cvt_pk_bf16_f32 v98, v98, v99
	v_cvt_pk_bf16_f32 v10, v10, v11
	v_perm_b32 v11, v10, v32, s97
	v_perm_b32 v10, v10, v32, s96
	v_pk_mul_f32 v[32:33], v[2:3], v[34:35] op_sel_hi:[0,1]
	v_pk_mul_f32 v[34:35], v[2:3], v[90:91] op_sel_hi:[0,1]
	v_pk_mul_f32 v[12:13], v[14:15], v[32:33]
	s_mov_b64 s[0:1], -1
	v_cvt_pk_bf16_f32 v2, v12, v13
	v_pk_mul_f32 v[12:13], v[16:17], v[34:35]
	s_and_b64 vcc, exec, s[80:81]
	v_cvt_pk_bf16_f32 v12, v12, v13
	v_perm_b32 v13, v12, v2, s97
	v_perm_b32 v12, v12, v2, s96
	v_cvt_pk_bf16_f32 v2, v0, v1
	v_pk_mul_f32 v[0:1], v[4:5], v[30:31]
	ds_write_b128 v159, v[10:13] offset:46080
	v_cvt_pk_bf16_f32 v0, v0, v1
	v_perm_b32 v5, v0, v2, s97
	v_perm_b32 v4, v0, v2, s96
	v_pk_mul_f32 v[0:1], v[6:7], v[32:33]
	v_mov_b32_e32 v12, s55
	v_cvt_pk_bf16_f32 v2, v0, v1
	v_pk_mul_f32 v[0:1], v[8:9], v[34:35]
	s_nop 0
	v_cvt_pk_bf16_f32 v0, v0, v1
	v_perm_b32 v7, v0, v2, s97
	v_perm_b32 v6, v0, v2, s96
	ds_write_b128 v159, v[4:7] offset:55296
	v_perm_b32 v5, v112, v113, s97
	v_perm_b32 v4, v112, v113, s96
	v_perm_b32 v7, v98, v105, s97
	v_perm_b32 v6, v98, v105, s96
	ds_write_b128 v159, v[4:7] offset:64512
	s_waitcnt lgkmcnt(0)
	s_barrier
	s_nop 0
	v_and_b32_e32 v0, 15, v28
	v_and_b32_e32 v1, -16, v28
	v_mad_u32_u24 v12, v0, s76, v12
	v_add_u32_e32 v30, v12, v1
	ds_read_b128 v[8:11], v140
	ds_read_b128 v[4:7], v140 offset:64
	ds_read_b128 v[16:19], v156
	ds_read_b128 v[12:15], v156 offset:64
	v_ashrrev_i32_e32 v2, 4, v28
	v_lshlrev_b32_e32 v29, 2, v2
	v_lshlrev_b32_e32 v2, 3, v2
	v_add_u32_e32 v33, s56, v2
	v_or_b32_e32 v89, v29, v69
	s_cbranch_vccz .LBB0_700
	s_waitcnt lgkmcnt(1)
	v_mfma_f32_16x16x32_bf16 v[94:97], v[16:19], v[8:11], 0
	s_mov_b64 s[0:1], 0
	s_waitcnt lgkmcnt(0)
	v_mfma_f32_16x16x32_bf16 v[94:97], v[12:15], v[4:7], v[94:97]
	s_nop 7
	v_bfi_b32 v35, v196, v94, v206
	v_and_b32_e32 v90, v166, v95
	v_cvt_pk_bf16_f32 v90, v35, v90
	v_and_b32_e32 v91, v199, v96
	v_and_b32_e32 v93, v202, v97
	v_cvt_pk_bf16_f32 v91, v91, v93
	ds_write_b64 v151, v[90:91]
